# attention mask mul_lo->mul_i24; RES epilogue pipelined with write-through (sc1) f32x4 stores
# speedup vs baseline: 1.0046x; 1.0046x over previous
.LBB0_495:
	v_add_u32_e32 v66, 0x2000, v213
	ds_read_b128 v[152:155], v212
	ds_read_b128 v[156:159], v212 offset:32
	ds_read_b128 v[160:163], v212 offset:64
	ds_read_b128 v[224:227], v212 offset:96
	ds_read2_b64 v[114:117], v213 offset1:2
	ds_read2_b64 v[118:121], v213 offset0:4 offset1:6
	ds_read2_b64 v[126:129], v66 offset0:64 offset1:66
	ds_read2_b64 v[122:125], v66 offset0:68 offset1:70
	s_waitcnt vmcnt(7) lgkmcnt(7)
	v_mfma_f32_32x32x16_bf16 v[66:81], v[152:155], v[82:85], 0
	v_add_u32_e32 v223, s11, v203
	v_add_u32_e32 v185, v204, v211
	s_add_i32 s11, s11, 32
	v_add_u32_e32 v213, 64, v213
	v_add_u32_e32 v212, 0x1200, v212
	s_cmpk_lg_i32 s11, 0x80
	s_waitcnt vmcnt(6) lgkmcnt(6)
	v_mfma_f32_32x32x16_bf16 v[66:81], v[156:159], v[86:89], v[66:81]
	s_waitcnt vmcnt(5) lgkmcnt(5)
	v_mfma_f32_32x32x16_bf16 v[66:81], v[160:163], v[90:93], v[66:81]
	s_waitcnt vmcnt(4) lgkmcnt(4)
	v_mfma_f32_32x32x16_bf16 v[66:81], v[224:227], v[94:97], v[66:81]
	s_nop 11
	v_mul_f32_e32 v66, 0x3fb8aa3b, v66
	v_exp_f32_e32 v148, v66
	v_mul_f32_e32 v66, 0x3fb8aa3b, v67
	v_exp_f32_e32 v180, v66
	v_mul_f32_e32 v66, 0x3fb8aa3b, v68
	v_exp_f32_e32 v181, v66
	v_mul_f32_e32 v66, 0x3fb8aa3b, v69
	v_exp_f32_e32 v182, v66
	v_mul_f32_e32 v66, 0x3fb8aa3b, v70
	v_exp_f32_e32 v183, v66
	v_mul_f32_e32 v66, 0x3fb8aa3b, v71
	v_exp_f32_e32 v184, v66
	v_mul_f32_e32 v66, 0x3fb8aa3b, v72
	v_exp_f32_e32 v149, v66
	v_mul_f32_e32 v66, 0x3fb8aa3b, v73
	v_exp_f32_e32 v222, v66
	v_mul_f32_e32 v66, 0x3fb8aa3b, v74
	v_exp_f32_e32 v221, v66
	v_mul_f32_e32 v66, 0x3fb8aa3b, v75
	v_exp_f32_e32 v220, v66
	v_mul_f32_e32 v66, 0x3fb8aa3b, v76
	v_exp_f32_e32 v219, v66
	v_mul_f32_e32 v66, 0x3fb8aa3b, v77
	v_exp_f32_e32 v218, v66
	v_mul_f32_e32 v66, 0x3fb8aa3b, v78
	v_exp_f32_e32 v217, v66
	v_mul_f32_e32 v66, 0x3fb8aa3b, v79
	v_exp_f32_e32 v216, v66
	v_mul_f32_e32 v66, 0x3fb8aa3b, v80
	v_exp_f32_e32 v215, v66
	v_mul_f32_e32 v66, 0x3fb8aa3b, v81
	v_exp_f32_e32 v214, v66
	s_waitcnt vmcnt(3)
	v_mfma_f32_32x32x16_bf16 v[66:81], v[152:155], v[98:101], 0
	v_mul_i32_i24_e32 v152, v223, v202
	v_add_u32_e32 v154, 2, v223
	v_mul_i32_i24_e32 v154, v154, v202
	s_waitcnt vmcnt(2)
	v_mfma_f32_32x32x16_bf16 v[66:81], v[156:159], v[102:105], v[66:81]
	s_waitcnt vmcnt(1)
	v_mfma_f32_32x32x16_bf16 v[66:81], v[160:163], v[106:109], v[66:81]
	s_waitcnt vmcnt(0)
	v_mfma_f32_32x32x16_bf16 v[66:81], v[224:227], v[110:113], v[66:81]
	v_add_u32_e32 v224, v206, v211
	v_add_u32_e32 v225, 17, v223
	s_nop 9
	v_mul_f32_e32 v70, 0x3fb8aa3b, v70
	v_exp_f32_e32 v158, v70
	v_mul_f32_e32 v70, 0x3fb8aa3b, v71
	v_mul_f32_e32 v66, 0x3fb8aa3b, v66
	v_exp_f32_e32 v71, v70
	v_add_u32_e32 v70, v210, v211
	v_exp_f32_e32 v66, v66
	v_cmp_lt_i32_e32 vcc, -1, v70
	v_mul_f32_e32 v67, 0x3fb8aa3b, v67
	v_exp_f32_e32 v67, v67
	v_cndmask_b32_e32 v70, 0, v149, vcc
	v_subrev_u32_e32 v149, 32, v223
	v_mul_i32_i24_e32 v149, v149, v202
	v_cmp_lt_i32_e32 vcc, -1, v149
	v_mul_f32_e32 v68, 0x3fb8aa3b, v68
	v_exp_f32_e32 v68, v68
	v_cndmask_b32_e32 v149, 0, v66, vcc
	v_subrev_u32_e32 v66, 31, v223
	v_cmp_lt_i32_e32 vcc, -1, v152
	v_mul_i32_i24_e32 v66, v66, v202
	v_mul_f32_e32 v69, 0x3fb8aa3b, v69
	v_cndmask_b32_e32 v148, 0, v148, vcc
	v_cmp_lt_i32_e32 vcc, -1, v66
	v_add_u32_e32 v152, v152, v202
	v_exp_f32_e32 v69, v69
	v_cndmask_b32_e32 v153, 0, v67, vcc
	v_subrev_u32_e32 v67, 30, v223
	v_cmp_lt_i32_e32 vcc, -1, v152
	v_mul_i32_i24_e32 v67, v67, v202
	v_pk_add_f32 v[162:163], v[148:149], 0 op_sel_hi:[1,0]
	v_cndmask_b32_e32 v152, 0, v180, vcc
	v_cmp_lt_i32_e32 vcc, -1, v67
	v_subrev_u32_e32 v67, 29, v223
	v_mul_i32_i24_e32 v67, v67, v202
	v_cndmask_b32_e32 v155, 0, v68, vcc
	v_cmp_lt_i32_e32 vcc, -1, v154
	v_add_u32_e32 v68, 3, v223
	v_mul_i32_i24_e32 v68, v68, v202
	v_cndmask_b32_e32 v154, 0, v181, vcc
	v_cmp_lt_i32_e32 vcc, -1, v67
	v_cvt_pk_bf16_f32 v66, v148, v152
	v_pk_add_f32 v[162:163], v[152:153], v[162:163]
	v_cndmask_b32_e32 v157, 0, v69, vcc
	v_cmp_lt_i32_e32 vcc, -1, v68
	v_subrev_u32_e32 v68, 24, v223
	v_add_u32_e32 v69, 8, v223
	v_mul_i32_i24_e32 v68, v68, v202
	v_cndmask_b32_e32 v156, 0, v182, vcc
	v_mul_i32_i24_e32 v69, v69, v202
	v_cmp_lt_i32_e32 vcc, -1, v68
	v_subrev_u32_e32 v68, 23, v223
	v_mul_i32_i24_e32 v68, v68, v202
	v_cndmask_b32_e32 v159, 0, v158, vcc
	v_cmp_lt_i32_e32 vcc, -1, v69
	v_add_u32_e32 v69, 9, v223
	v_mul_i32_i24_e32 v69, v69, v202
	v_cndmask_b32_e32 v158, 0, v183, vcc
	v_cmp_lt_i32_e32 vcc, -1, v68
	v_pk_add_f32 v[162:163], v[154:155], v[162:163]
	v_cvt_pk_bf16_f32 v67, v154, v156
	v_cndmask_b32_e32 v161, 0, v71, vcc
	v_mul_f32_e32 v71, 0x3fb8aa3b, v72
	v_exp_f32_e32 v71, v71
	v_mul_f32_e32 v72, 0x3fb8aa3b, v73
	v_exp_f32_e32 v148, v72
	v_cmp_lt_i32_e32 vcc, -1, v69
	v_add_u32_e32 v69, v207, v211
	v_mul_f32_e32 v72, 0x3fb8aa3b, v74
	v_cndmask_b32_e32 v160, 0, v184, vcc
	v_cmp_lt_i32_e32 vcc, -1, v69
	v_add_u32_e32 v69, v208, v211
	v_exp_f32_e32 v74, v72
	v_mul_f32_e32 v72, 0x3fb8aa3b, v75
	v_cndmask_b32_e32 v71, 0, v71, vcc
	v_exp_f32_e32 v75, v72
	v_mul_f32_e32 v72, 0x3fb8aa3b, v76
	v_cmp_lt_i32_e32 vcc, -1, v69
	v_pk_add_f32 v[162:163], v[156:157], v[162:163]
	v_add_u32_e32 v152, v209, v211
	v_exp_f32_e32 v156, v72
	v_mul_f32_e32 v72, 0x3fb8aa3b, v77
	v_cndmask_b32_e32 v77, 0, v148, vcc
	v_cmp_lt_i32_e32 vcc, -1, v185
	v_cvt_pk_bf16_f32 v68, v158, v160
	v_pk_add_f32 v[162:163], v[158:159], v[162:163]
	v_add_u32_e32 v154, -15, v223
	v_exp_f32_e32 v158, v72
	v_mul_f32_e32 v72, 0x3fb8aa3b, v78
	v_cndmask_b32_e32 v76, 0, v222, vcc
	v_cmp_lt_i32_e32 vcc, -1, v152
	v_pk_add_f32 v[162:163], v[160:161], v[162:163]
	v_exp_f32_e32 v160, v72
	v_mul_f32_e32 v72, 0x3fb8aa3b, v79
	v_cndmask_b32_e32 v79, 0, v74, vcc
	v_cmp_lt_i32_e32 vcc, -1, v224
	v_mul_i32_i24_e32 v74, v154, v202
	v_exp_f32_e32 v184, v72
	v_mul_f32_e32 v72, 0x3fb8aa3b, v80
	v_cndmask_b32_e32 v78, 0, v221, vcc
	v_mul_i32_i24_e32 v69, v225, v202
	v_cmp_lt_i32_e32 vcc, -1, v74
	v_exp_f32_e32 v226, v72
	v_mul_f32_e32 v72, 0x3fb8aa3b, v81
	v_cndmask_b32_e32 v81, 0, v75, vcc
	v_cmp_lt_i32_e32 vcc, -1, v69
	v_add_u32_e32 v69, -14, v223
	v_add_u32_e32 v74, 18, v223
	v_mul_i32_i24_e32 v69, v69, v202
	v_cndmask_b32_e32 v80, 0, v220, vcc
	v_mul_i32_i24_e32 v74, v74, v202
	v_cmp_lt_i32_e32 vcc, -1, v69
	v_add_u32_e32 v69, -13, v223
	v_exp_f32_e32 v227, v72
	v_pk_add_f32 v[72:73], v[70:71], v[162:163]
	v_cndmask_b32_e32 v163, 0, v156, vcc
	v_cmp_lt_i32_e32 vcc, -1, v74
	v_add_u32_e32 v74, 19, v223
	v_mul_i32_i24_e32 v69, v69, v202
	v_cndmask_b32_e32 v162, 0, v219, vcc
	v_mul_i32_i24_e32 v74, v74, v202
	v_cmp_lt_i32_e32 vcc, -1, v69
	v_add_u32_e32 v69, -8, v223
	v_mul_i32_i24_e32 v69, v69, v202
	v_cndmask_b32_e32 v181, 0, v158, vcc
	v_cmp_lt_i32_e32 vcc, -1, v74
	v_add_u32_e32 v74, 24, v223
	v_mul_i32_i24_e32 v74, v74, v202
	v_cndmask_b32_e32 v180, 0, v218, vcc
	v_cmp_lt_i32_e32 vcc, -1, v69
	v_add_u32_e32 v69, -7, v223
	v_mul_i32_i24_e32 v69, v69, v202
	v_cndmask_b32_e32 v183, 0, v160, vcc
	v_cmp_lt_i32_e32 vcc, -1, v74
	v_add_u32_e32 v74, 25, v223
	v_mul_i32_i24_e32 v74, v74, v202
	v_cndmask_b32_e32 v182, 0, v217, vcc
	v_cmp_lt_i32_e32 vcc, -1, v69
	v_add_u32_e32 v69, -6, v223
	v_mul_i32_i24_e32 v69, v69, v202
	v_cndmask_b32_e32 v185, 0, v184, vcc
	v_cmp_lt_i32_e32 vcc, -1, v74
	v_add_u32_e32 v74, 26, v223
	v_mul_i32_i24_e32 v74, v74, v202
	v_cndmask_b32_e32 v184, 0, v216, vcc
	v_cmp_lt_i32_e32 vcc, -1, v69
	v_add_u32_e32 v69, -5, v223
	v_mul_i32_i24_e32 v69, v69, v202
	v_cndmask_b32_e32 v217, 0, v226, vcc
	v_cmp_lt_i32_e32 vcc, -1, v74
	v_pk_add_f32 v[72:73], v[76:77], v[72:73]
	v_add_u32_e32 v74, 27, v223
	v_cndmask_b32_e32 v216, 0, v215, vcc
	v_cmp_lt_i32_e32 vcc, -1, v69
	v_cvt_pk_bf16_f32 v69, v70, v76
	v_pk_add_f32 v[72:73], v[78:79], v[72:73]
	v_mul_i32_i24_e32 v74, v74, v202
	v_pk_add_f32 v[72:73], v[80:81], v[72:73]
	s_waitcnt lgkmcnt(3)
	v_mfma_f32_32x32x16_bf16 v[34:49], v[66:69], v[114:117], v[34:49]
	v_add_f32_e64 v72, v162, v72
	v_add_f32_e64 v73, v163, v73
	v_cndmask_b32_e32 v215, 0, v227, vcc
	v_add_f32_e64 v72, v180, v72
	v_add_f32_e64 v73, v181, v73
	v_cmp_lt_i32_e32 vcc, -1, v74
	v_pk_add_f32 v[72:73], v[182:183], v[72:73]
	v_cvt_pk_bf16_f32 v74, v182, v184
	v_pk_add_f32 v[72:73], v[184:185], v[72:73]
	s_waitcnt lgkmcnt(1)
	v_mfma_f32_32x32x16_bf16 v[50:65], v[66:69], v[126:129], v[50:65]
	v_cvt_pk_bf16_f32 v66, v149, v153
	v_cvt_pk_bf16_f32 v67, v155, v157
	v_cvt_pk_bf16_f32 v68, v159, v161
	v_cvt_pk_bf16_f32 v69, v71, v77
	v_add_f32_e64 v72, v216, v72
	v_add_f32_e64 v73, v217, v73
	v_cndmask_b32_e32 v214, 0, v214, vcc
	v_pk_add_f32 v[218:219], v[214:215], v[72:73]
	v_cvt_pk_bf16_f32 v72, v78, v80
	v_cvt_pk_bf16_f32 v73, v162, v180
	v_cvt_pk_bf16_f32 v75, v216, v214
	v_mfma_f32_32x32x16_bf16 v[18:33], v[66:69], v[114:117], v[18:33]
	v_cvt_pk_bf16_f32 v70, v79, v81
	v_cvt_pk_bf16_f32 v71, v163, v181
	v_add_f32_e64 v130, v130, v218
	v_add_f32_e64 v131, v131, v219
	v_add_u32_e32 v211, v211, v205
	v_mfma_f32_32x32x16_bf16 v[2:17], v[66:69], v[126:129], v[2:17]
	v_mfma_f32_32x32x16_bf16 v[34:49], v[72:75], v[118:121], v[34:49]
	s_waitcnt lgkmcnt(0)
	v_mfma_f32_32x32x16_bf16 v[50:65], v[72:75], v[122:125], v[50:65]
	v_cvt_pk_bf16_f32 v72, v183, v185
	v_cvt_pk_bf16_f32 v73, v217, v215
	s_nop 1
	v_mfma_f32_32x32x16_bf16 v[18:33], v[70:73], v[118:121], v[18:33]
	v_mfma_f32_32x32x16_bf16 v[2:17], v[70:73], v[122:125], v[2:17]
	s_cbranch_scc1 .LBB0_495
	s_branch .LBB0_492

.Lres_fast:
	s_mov_b64 s[4:5], 0x10000
	s_mov_b64 s[6:7], 0x50000
	global_load_dwordx4 v[206:209], v[172:173], off
	global_load_dwordx4 v[210:213], v[172:173], off offset:64
	global_load_dwordx4 v[214:217], v[172:173], off offset:512
	global_load_dwordx4 v[218:221], v[172:173], off offset:576
	v_lshl_add_u64 v[172:173], v[172:173], 0, s[4:5]
	global_load_dwordx4 v[222:225], v[172:173], off
	global_load_dwordx4 v[226:229], v[172:173], off offset:64
	global_load_dwordx4 v[236:239], v[172:173], off offset:512
	global_load_dwordx4 v[240:243], v[172:173], off offset:576
	v_lshl_add_u64 v[172:173], v[172:173], 0, s[4:5]
	global_load_dwordx4 v[244:247], v[172:173], off
	global_load_dwordx4 v[146:149], v[172:173], off offset:64
	global_load_dwordx4 v[168:171], v[172:173], off offset:512
	global_load_dwordx4 v[164:167], v[172:173], off offset:576
	v_lshl_add_u64 v[172:173], v[172:173], 0, s[4:5]
	s_waitcnt vmcnt(8)
	v_pk_fma_f32 v[206:207], v[126:127], v[142:143], v[206:207]
	v_pk_fma_f32 v[208:209], v[128:129], v[144:145], v[208:209]
	v_pk_fma_f32 v[210:211], v[118:119], v[138:139], v[210:211]
	v_pk_fma_f32 v[212:213], v[120:121], v[140:141], v[212:213]
	v_pk_fma_f32 v[214:215], v[122:123], v[134:135], v[214:215]
	v_pk_fma_f32 v[216:217], v[124:125], v[136:137], v[216:217]
	v_pk_fma_f32 v[218:219], v[114:115], v[130:131], v[218:219]
	v_pk_fma_f32 v[220:221], v[116:117], v[132:133], v[220:221]
	global_store_dwordx4 v[174:175], v[206:209], off sc1
	global_store_dwordx4 v[174:175], v[210:213], off offset:64 sc1
	global_store_dwordx4 v[174:175], v[214:217], off offset:512 sc1
	global_store_dwordx4 v[174:175], v[218:221], off offset:576 sc1
	v_lshl_add_u64 v[174:175], v[174:175], 0, s[4:5]
	global_load_dwordx4 v[206:209], v[172:173], off
	global_load_dwordx4 v[210:213], v[172:173], off offset:64
	global_load_dwordx4 v[214:217], v[172:173], off offset:512
	global_load_dwordx4 v[218:221], v[172:173], off offset:576
	v_lshl_add_u64 v[172:173], v[172:173], 0, s[6:7]
	s_waitcnt vmcnt(12)
	v_pk_fma_f32 v[222:223], v[110:111], v[142:143], v[222:223]
	v_pk_fma_f32 v[224:225], v[112:113], v[144:145], v[224:225]
	v_pk_fma_f32 v[226:227], v[102:103], v[138:139], v[226:227]
	v_pk_fma_f32 v[228:229], v[104:105], v[140:141], v[228:229]
	v_pk_fma_f32 v[236:237], v[106:107], v[134:135], v[236:237]
	v_pk_fma_f32 v[238:239], v[108:109], v[136:137], v[238:239]
	v_pk_fma_f32 v[240:241], v[98:99], v[130:131], v[240:241]
	v_pk_fma_f32 v[242:243], v[100:101], v[132:133], v[242:243]
	global_store_dwordx4 v[174:175], v[222:225], off sc1
	global_store_dwordx4 v[174:175], v[226:229], off offset:64 sc1
	global_store_dwordx4 v[174:175], v[236:239], off offset:512 sc1
	global_store_dwordx4 v[174:175], v[240:243], off offset:576 sc1
	v_lshl_add_u64 v[174:175], v[174:175], 0, s[4:5]
	global_load_dwordx4 v[222:225], v[172:173], off
	global_load_dwordx4 v[226:229], v[172:173], off offset:64
	global_load_dwordx4 v[236:239], v[172:173], off offset:512
	global_load_dwordx4 v[240:243], v[172:173], off offset:576
	v_lshl_add_u64 v[172:173], v[172:173], 0, s[4:5]
	s_waitcnt vmcnt(16)
	v_pk_fma_f32 v[244:245], v[94:95], v[142:143], v[244:245]
	v_pk_fma_f32 v[246:247], v[96:97], v[144:145], v[246:247]
	v_pk_fma_f32 v[146:147], v[86:87], v[138:139], v[146:147]
	v_pk_fma_f32 v[148:149], v[88:89], v[140:141], v[148:149]
	v_pk_fma_f32 v[168:169], v[90:91], v[134:135], v[168:169]
	v_pk_fma_f32 v[170:171], v[92:93], v[136:137], v[170:171]
	v_pk_fma_f32 v[164:165], v[82:83], v[130:131], v[164:165]
	v_pk_fma_f32 v[166:167], v[84:85], v[132:133], v[166:167]
	global_store_dwordx4 v[174:175], v[244:247], off sc1
	global_store_dwordx4 v[174:175], v[146:149], off offset:64 sc1
	global_store_dwordx4 v[174:175], v[168:171], off offset:512 sc1
	global_store_dwordx4 v[174:175], v[164:167], off offset:576 sc1
	v_lshl_add_u64 v[174:175], v[174:175], 0, s[4:5]
	global_load_dwordx4 v[244:247], v[172:173], off
	global_load_dwordx4 v[146:149], v[172:173], off offset:64
	global_load_dwordx4 v[168:171], v[172:173], off offset:512
	global_load_dwordx4 v[164:167], v[172:173], off offset:576
	v_lshl_add_u64 v[172:173], v[172:173], 0, s[4:5]
	s_waitcnt vmcnt(16)
	v_pk_fma_f32 v[206:207], v[78:79], v[142:143], v[206:207]
	v_pk_fma_f32 v[208:209], v[80:81], v[144:145], v[208:209]
	v_pk_fma_f32 v[210:211], v[70:71], v[138:139], v[210:211]
	v_pk_fma_f32 v[212:213], v[72:73], v[140:141], v[212:213]
	v_pk_fma_f32 v[214:215], v[74:75], v[134:135], v[214:215]
	v_pk_fma_f32 v[216:217], v[76:77], v[136:137], v[216:217]
	v_pk_fma_f32 v[218:219], v[66:67], v[130:131], v[218:219]
	v_pk_fma_f32 v[220:221], v[68:69], v[132:133], v[220:221]
	global_store_dwordx4 v[174:175], v[206:209], off sc1
	global_store_dwordx4 v[174:175], v[210:213], off offset:64 sc1
	global_store_dwordx4 v[174:175], v[214:217], off offset:512 sc1
	global_store_dwordx4 v[174:175], v[218:221], off offset:576 sc1
	v_lshl_add_u64 v[174:175], v[174:175], 0, s[6:7]
	global_load_dwordx4 v[206:209], v[172:173], off
	global_load_dwordx4 v[210:213], v[172:173], off offset:64
	global_load_dwordx4 v[214:217], v[172:173], off offset:512
	global_load_dwordx4 v[218:221], v[172:173], off offset:576
	v_lshl_add_u64 v[172:173], v[172:173], 0, s[4:5]
	s_waitcnt vmcnt(16)
	v_pk_fma_f32 v[222:223], v[62:63], v[142:143], v[222:223]
	v_pk_fma_f32 v[224:225], v[64:65], v[144:145], v[224:225]
	v_pk_fma_f32 v[226:227], v[54:55], v[138:139], v[226:227]
	v_pk_fma_f32 v[228:229], v[56:57], v[140:141], v[228:229]
	v_pk_fma_f32 v[236:237], v[58:59], v[134:135], v[236:237]
	v_pk_fma_f32 v[238:239], v[60:61], v[136:137], v[238:239]
	v_pk_fma_f32 v[240:241], v[50:51], v[130:131], v[240:241]
	v_pk_fma_f32 v[242:243], v[52:53], v[132:133], v[242:243]
	global_store_dwordx4 v[174:175], v[222:225], off sc1
	global_store_dwordx4 v[174:175], v[226:229], off offset:64 sc1
	global_store_dwordx4 v[174:175], v[236:239], off offset:512 sc1
	global_store_dwordx4 v[174:175], v[240:243], off offset:576 sc1
	v_lshl_add_u64 v[174:175], v[174:175], 0, s[4:5]
	global_load_dwordx4 v[222:225], v[172:173], off
	global_load_dwordx4 v[226:229], v[172:173], off offset:64
	global_load_dwordx4 v[236:239], v[172:173], off offset:512
	global_load_dwordx4 v[240:243], v[172:173], off offset:576
	s_waitcnt vmcnt(16)
	v_pk_fma_f32 v[244:245], v[46:47], v[142:143], v[244:245]
	v_pk_fma_f32 v[246:247], v[48:49], v[144:145], v[246:247]
	v_pk_fma_f32 v[146:147], v[38:39], v[138:139], v[146:147]
	v_pk_fma_f32 v[148:149], v[40:41], v[140:141], v[148:149]
	v_pk_fma_f32 v[168:169], v[42:43], v[134:135], v[168:169]
	v_pk_fma_f32 v[170:171], v[44:45], v[136:137], v[170:171]
	v_pk_fma_f32 v[164:165], v[34:35], v[130:131], v[164:165]
	v_pk_fma_f32 v[166:167], v[36:37], v[132:133], v[166:167]
	global_store_dwordx4 v[174:175], v[244:247], off sc1
	global_store_dwordx4 v[174:175], v[146:149], off offset:64 sc1
	global_store_dwordx4 v[174:175], v[168:171], off offset:512 sc1
	global_store_dwordx4 v[174:175], v[164:167], off offset:576 sc1
	v_lshl_add_u64 v[174:175], v[174:175], 0, s[4:5]
	s_waitcnt vmcnt(12)
	v_pk_fma_f32 v[206:207], v[30:31], v[142:143], v[206:207]
	v_pk_fma_f32 v[208:209], v[32:33], v[144:145], v[208:209]
	v_pk_fma_f32 v[210:211], v[22:23], v[138:139], v[210:211]
	v_pk_fma_f32 v[212:213], v[24:25], v[140:141], v[212:213]
	v_pk_fma_f32 v[214:215], v[26:27], v[134:135], v[214:215]
	v_pk_fma_f32 v[216:217], v[28:29], v[136:137], v[216:217]
	v_pk_fma_f32 v[218:219], v[18:19], v[130:131], v[218:219]
	v_pk_fma_f32 v[220:221], v[20:21], v[132:133], v[220:221]
	global_store_dwordx4 v[174:175], v[206:209], off sc1
	global_store_dwordx4 v[174:175], v[210:213], off offset:64 sc1
	global_store_dwordx4 v[174:175], v[214:217], off offset:512 sc1
	global_store_dwordx4 v[174:175], v[218:221], off offset:576 sc1
	v_lshl_add_u64 v[174:175], v[174:175], 0, s[4:5]
	s_waitcnt vmcnt(8)
	v_pk_fma_f32 v[222:223], v[14:15], v[142:143], v[222:223]
	v_pk_fma_f32 v[224:225], v[16:17], v[144:145], v[224:225]
	v_pk_fma_f32 v[226:227], v[6:7], v[138:139], v[226:227]
	v_pk_fma_f32 v[228:229], v[8:9], v[140:141], v[228:229]
	v_pk_fma_f32 v[236:237], v[10:11], v[134:135], v[236:237]
	v_pk_fma_f32 v[238:239], v[12:13], v[136:137], v[238:239]
	v_pk_fma_f32 v[240:241], v[2:3], v[130:131], v[240:241]
	v_pk_fma_f32 v[242:243], v[4:5], v[132:133], v[242:243]
	global_store_dwordx4 v[174:175], v[222:225], off sc1
	global_store_dwordx4 v[174:175], v[226:229], off offset:64 sc1
	global_store_dwordx4 v[174:175], v[236:239], off offset:512 sc1
	global_store_dwordx4 v[174:175], v[240:243], off offset:576 sc1
	s_branch .LBB0_816

.LBB0_1041:
	s_andn2_b64 vcc, exec, s[6:7]
	s_cbranch_vccnz .LBB0_1043
	global_load_dwordx4 v[130:133], v[130:131], off offset:64
	s_nop 0
	global_load_dwordx4 v[134:137], v[134:135], off offset:64
	s_waitcnt vmcnt(0)
	s_branch .LBB0_1044

.LBB0_1044:
	v_pk_add_f32 v[128:129], v[128:129], v[144:145]
	v_pk_add_f32 v[126:127], v[126:127], v[142:143]
	v_pk_add_f32 v[162:163], v[124:125], v[140:141]
	v_pk_add_f32 v[164:165], v[122:123], v[138:139]
	s_mov_b64 s[6:7], -1
	s_and_b64 vcc, exec, s[2:3]
	s_cbranch_vccz .LBB0_1046
	v_mul_f32_e32 v122, 0xbfb8aa3b, v126
	v_mul_f32_e32 v123, 0xbfb8aa3b, v127
	v_exp_f32_e32 v122, v122
	v_exp_f32_e32 v123, v123
	v_mul_f32_e32 v124, 0xbfb8aa3b, v128
	v_mul_f32_e32 v125, 0xbfb8aa3b, v129
	v_exp_f32_e32 v124, v124
	v_pk_add_f32 v[122:123], v[122:123], 1.0 op_sel_hi:[1,0]
	v_exp_f32_e32 v125, v125
	v_rcp_f32_e32 v166, v123
	v_pk_add_f32 v[124:125], v[124:125], 1.0 op_sel_hi:[1,0]
	s_mov_b64 s[6:7], 0
	v_mul_f32_e32 v123, v127, v166
	v_rcp_f32_e32 v166, v122
	s_nop 0
	v_mul_f32_e32 v122, v126, v166
	v_rcp_f32_e32 v166, v125
	v_pk_mul_f32 v[122:123], v[164:165], v[122:123]
	v_mul_f32_e32 v125, v129, v166
	v_rcp_f32_e32 v166, v124
	s_nop 0
	v_mul_f32_e32 v124, v128, v166
	v_pk_mul_f32 v[124:125], v[162:163], v[124:125]
